# v107 + attention loop: uniform prefetch-flag inversion done with one s_andn2 instead of v_cndmask + v_cmp (2 VALU fewer per KV block)
# baseline (speedup 1.0000x reference)
.LBB0_315:
	s_waitcnt lgkmcnt(14)
	v_mfma_f32_32x32x16_bf16 v[16:31], v[144:147], v[196:199], v[16:31]
	v_exp_f32_e32 v48, v48
	v_exp_f32_e32 v49, v49
	v_exp_f32_e32 v50, v50
	v_exp_f32_e32 v51, v51
	s_waitcnt lgkmcnt(12)
	v_mfma_f32_32x32x16_bf16 v[0:15], v[144:147], v[192:195], v[0:15]
	v_exp_f32_e32 v52, v52
	v_exp_f32_e32 v53, v53
	v_exp_f32_e32 v54, v54
	v_exp_f32_e32 v55, v55
	s_andn2_b64 s[8:9], exec, s[66:67]
	s_andn2_b64 vcc, exec, s[66:67]
	v_add_u32_e32 v72, s43, v238
	s_cbranch_vccnz .LBB0_317
	ds_read_b128 v[184:187], v72
	ds_read_b128 v[176:179], v72 offset:512
	v_add_u32_e32 v73, v239, v247
	v_add_u32_e32 v74, v239, v248
	ds_read_b128 v[152:155], v73
	ds_read_b128 v[148:151], v74
